# P1 input-row loads: flat loads converted to global loads (on v73)
# speedup vs baseline: 1.0055x; 1.0039x over previous
; __device__ __forceinline__ void norm_mod_phase(const Ctx& F, const float* xin, const float* gain, const float* shift, const float* scale) {
;     ...
;             for (int u = 0; u < 4; ++u) { const float* xr = xin + (size_t)(row0 + r + u) * D; s[u] = 0.f;
; #pragma unroll
;                 for (int j = 0; j < 4; ++j) v[u][j] = *(const f32x4*)(xr + 4 * ln + 256 * j); }
; #pragma unroll
;             for (int u = 0; u < 4; ++u) {
; #pragma unroll
;                 for (int j = 0; j < 4; ++j) s[u] += (v[u][j][0] * v[u][j][0] + v[u][j][1] * v[u][j][1]) + (v[u][j][2] * v[u][j][2] + v[u][j][3] * v[u][j][3]);
.LBB0_164:
	v_lshl_add_u64 v[28:29], s[36:37], 0, v[80:81]
	v_lshl_add_u64 v[30:31], s[40:41], 0, v[80:81]
	v_lshl_add_u64 v[106:107], s[54:55], 0, v[80:81]
	v_lshl_add_u64 v[110:111], s[30:31], 0, v[80:81]
	global_load_dwordx4 v[76:79], v[28:29], off nt
	global_load_dwordx4 v[68:71], v[28:29], off offset:1024 nt
	global_load_dwordx4 v[64:67], v[28:29], off offset:3072 nt
	global_load_dwordx4 v[72:75], v[28:29], off offset:2048 nt
	global_load_dwordx4 v[60:63], v[30:31], off nt
	global_load_dwordx4 v[56:59], v[30:31], off offset:1024 nt
	global_load_dwordx4 v[52:55], v[30:31], off offset:2048 nt
	global_load_dwordx4 v[48:51], v[30:31], off offset:3072 nt
	global_load_dwordx4 v[44:47], v[106:107], off nt
	global_load_dwordx4 v[40:43], v[106:107], off offset:1024 nt
	global_load_dwordx4 v[36:39], v[106:107], off offset:2048 nt
	global_load_dwordx4 v[32:35], v[106:107], off offset:3072 nt
	global_load_dwordx4 v[24:27], v[110:111], off nt
	global_load_dwordx4 v[20:23], v[110:111], off offset:1024 nt
	global_load_dwordx4 v[16:19], v[110:111], off offset:2048 nt
	global_load_dwordx4 v[28:31], v[110:111], off offset:3072 nt
	v_lshl_add_u64 v[108:109], s[28:29], 0, v[88:89]
	v_add_co_u32_e32 v112, vcc, s42, v108
	v_lshl_add_u64 v[118:119], s[38:39], 0, v[88:89]
	s_nop 0
	v_addc_co_u32_e32 v113, vcc, 0, v109, vcc
	v_add_co_u32_e32 v110, vcc, s42, v118
	v_lshl_add_u64 v[120:121], s[52:53], 0, v[88:89]
	s_nop 0
	v_addc_co_u32_e32 v111, vcc, 0, v119, vcc
	v_add_co_u32_e32 v108, vcc, s42, v120
	v_lshl_add_u64 v[122:123], s[34:35], 0, v[88:89]
	s_nop 0
	v_addc_co_u32_e32 v109, vcc, 0, v121, vcc
	v_add_co_u32_e32 v106, vcc, s42, v122
	s_add_u32 s28, s28, 0x2000
	s_nop 0
	v_addc_co_u32_e32 v107, vcc, 0, v123, vcc
	s_addc_u32 s29, s29, 0
	s_add_i32 s21, s21, 4
	s_add_u32 s30, s30, 0x4000
	s_addc_u32 s31, s31, 0
	s_add_u32 s34, s34, 0x2000
	s_addc_u32 s35, s35, 0
	s_add_u32 s36, s36, 0x4000
	s_addc_u32 s37, s37, 0
	s_add_u32 s38, s38, 0x2000
	s_addc_u32 s39, s39, 0
	s_add_u32 s40, s40, 0x4000
	s_addc_u32 s41, s41, 0
	s_add_u32 s52, s52, 0x2000
	s_addc_u32 s53, s53, 0
	s_add_u32 s54, s54, 0x4000
	s_addc_u32 s55, s55, 0
	s_cmp_gt_u32 s21, 27
	s_waitcnt vmcnt(0) lgkmcnt(0)
	v_pk_mul_f32 v[118:119], v[78:79], v[78:79]
	v_pk_mul_f32 v[120:121], v[76:77], v[76:77]
	v_pk_mul_f32 v[122:123], v[70:71], v[70:71]
	v_pk_mul_f32 v[124:125], v[68:69], v[68:69]
	v_mul_f32_e32 v126, v73, v73
	v_mul_f32_e32 v128, v75, v75
	v_pk_mul_f32 v[130:131], v[62:63], v[62:63]
	v_pk_mul_f32 v[132:133], v[60:61], v[60:61]
	v_pk_mul_f32 v[134:135], v[58:59], v[58:59]
	v_pk_mul_f32 v[136:137], v[56:57], v[56:57]
	v_mul_f32_e32 v138, v53, v53
	v_mul_f32_e32 v140, v55, v55
	v_pk_mul_f32 v[142:143], v[46:47], v[46:47]
	v_pk_mul_f32 v[144:145], v[44:45], v[44:45]
	v_pk_mul_f32 v[146:147], v[42:43], v[42:43]
	v_pk_mul_f32 v[148:149], v[40:41], v[40:41]
	v_pk_mov_b32 v[166:167], v[120:121], v[118:119] op_sel:[1,0]
	v_mov_b32_e32 v121, v119
	v_pk_mov_b32 v[118:119], v[124:125], v[122:123] op_sel:[1,0]
	v_mov_b32_e32 v125, v123
	v_mul_f32_e32 v150, v37, v37
	v_mul_f32_e32 v152, v39, v39
	v_pk_mul_f32 v[154:155], v[26:27], v[26:27]
	v_pk_mul_f32 v[156:157], v[24:25], v[24:25]
	v_pk_mul_f32 v[158:159], v[22:23], v[22:23]
	v_pk_mul_f32 v[160:161], v[20:21], v[20:21]
	v_pk_fma_f32 v[122:123], v[72:73], v[72:73], v[126:127] op_sel_hi:[1,1,0]
	v_pk_fma_f32 v[126:127], v[74:75], v[74:75], v[128:129] op_sel_hi:[1,1,0]
	v_pk_mov_b32 v[128:129], v[132:133], v[130:131] op_sel:[1,0]
	v_mov_b32_e32 v133, v131
	v_pk_mov_b32 v[130:131], v[136:137], v[134:135] op_sel:[1,0]
	v_mov_b32_e32 v137, v135
	v_pk_fma_f32 v[134:135], v[52:53], v[52:53], v[138:139] op_sel_hi:[1,1,0]
	v_pk_fma_f32 v[138:139], v[54:55], v[54:55], v[140:141] op_sel_hi:[1,1,0]
	v_pk_mov_b32 v[140:141], v[144:145], v[142:143] op_sel:[1,0]
	v_mov_b32_e32 v145, v143
	v_pk_mov_b32 v[142:143], v[148:149], v[146:147] op_sel:[1,0]
	v_mov_b32_e32 v149, v147
	v_pk_add_f32 v[120:121], v[166:167], v[120:121]
	v_pk_add_f32 v[118:119], v[118:119], v[124:125]
	v_mul_f32_e32 v117, v66, v66
	v_mul_f32_e32 v165, v67, v67
	v_mul_f32_e32 v168, v64, v64
	v_mul_f32_e32 v169, v65, v65
	v_pk_fma_f32 v[146:147], v[36:37], v[36:37], v[150:151] op_sel_hi:[1,1,0]
	v_pk_fma_f32 v[150:151], v[38:39], v[38:39], v[152:153] op_sel_hi:[1,1,0]
	v_pk_mov_b32 v[152:153], v[156:157], v[154:155] op_sel:[1,0]
	v_mov_b32_e32 v157, v155
	v_pk_mov_b32 v[154:155], v[160:161], v[158:159] op_sel:[1,0]
	v_mov_b32_e32 v161, v159
	v_pk_add_f32 v[124:125], v[128:129], v[132:133]
	v_pk_add_f32 v[128:129], v[130:131], v[136:137]
	v_pk_add_f32 v[130:131], v[140:141], v[144:145]
	v_pk_add_f32 v[132:133], v[142:143], v[148:149]
	v_pk_add_f32 v[120:121], v[120:121], v[120:121] op_sel:[0,1] op_sel_hi:[1,0]
	v_pk_add_f32 v[118:119], v[118:119], v[118:119] op_sel:[0,1] op_sel_hi:[1,0]
	v_mul_f32_e32 v170, v50, v50
	v_mul_f32_e32 v171, v51, v51
	v_mul_f32_e32 v172, v48, v48
	v_mul_f32_e32 v173, v49, v49
	v_mul_f32_e32 v174, v34, v34
	v_mul_f32_e32 v175, v35, v35
	v_mul_f32_e32 v176, v32, v32
	v_mul_f32_e32 v177, v33, v33
	v_mul_f32_e32 v162, v17, v17
	v_mul_f32_e32 v164, v19, v19
	v_mov_b32_e32 v123, v117
	v_mov_b32_e32 v127, v165
	v_pk_add_f32 v[136:137], v[152:153], v[156:157]
	v_pk_add_f32 v[140:141], v[154:155], v[160:161]
	v_pk_add_f32 v[124:125], v[124:125], v[124:125] op_sel:[0,1] op_sel_hi:[1,0]
	v_pk_add_f32 v[128:129], v[128:129], v[128:129] op_sel:[0,1] op_sel_hi:[1,0]
	v_pk_add_f32 v[130:131], v[130:131], v[130:131] op_sel:[0,1] op_sel_hi:[1,0]
	v_pk_add_f32 v[132:133], v[132:133], v[132:133] op_sel:[0,1] op_sel_hi:[1,0]
	v_mov_b32_e32 v121, v168
	v_mov_b32_e32 v119, v169
; __device__ __forceinline__ float wave_sum_fast(float x) { x = reduce16(x); return (rl_(x, 0) + rl_(x, 16)) + (rl_(x, 32) + rl_(x, 48)); }
; __device__ __forceinline__ void norm_mod_phase(const Ctx& F, const float* xin, const float* gain, const float* shift, const float* scale) {
;     ...
;                 for (int j = 0; j < 4; ++j) s[u] += (v[u][j][0] * v[u][j][0] + v[u][j][1] * v[u][j][1]) + (v[u][j][2] * v[u][j][2] + v[u][j][3] * v[u][j][3]);
;                 s[u] = wave_sum_fast(s[u]); }
; #pragma unroll
;             for (int u = 0; u < 4; ++u) { const float rstd = 1.0f / sqrtf(s[u] * (1.0f / D) + 1e-6f);
	v_mul_f32_e32 v178, v30, v30
	v_mul_f32_e32 v179, v31, v31
	v_mul_f32_e32 v180, v28, v28
	v_mul_f32_e32 v181, v29, v29
	v_pk_fma_f32 v[158:159], v[16:17], v[16:17], v[162:163] op_sel_hi:[1,1,0]
	v_pk_fma_f32 v[162:163], v[18:19], v[18:19], v[164:165] op_sel_hi:[1,1,0]
	v_mov_b32_e32 v135, v170
	v_mov_b32_e32 v139, v171
	v_mov_b32_e32 v147, v174
	v_mov_b32_e32 v151, v175
	v_pk_add_f32 v[122:123], v[122:123], v[126:127]
	v_pk_add_f32 v[136:137], v[136:137], v[136:137] op_sel:[0,1] op_sel_hi:[1,0]
	v_pk_add_f32 v[140:141], v[140:141], v[140:141] op_sel:[0,1] op_sel_hi:[1,0]
	v_mov_b32_e32 v125, v172
	v_mov_b32_e32 v129, v173
	v_mov_b32_e32 v131, v176
	v_mov_b32_e32 v133, v177
	v_pk_add_f32 v[118:119], v[120:121], v[118:119]
	v_mov_b32_e32 v159, v178
	v_mov_b32_e32 v163, v179
	v_pk_add_f32 v[126:127], v[134:135], v[138:139]
	v_pk_add_f32 v[134:135], v[146:147], v[150:151]
	v_mov_b32_e32 v137, v180
	v_mov_b32_e32 v141, v181
	v_pk_add_f32 v[120:121], v[124:125], v[128:129]
	v_pk_add_f32 v[124:125], v[130:131], v[132:133]
	v_pk_add_f32 v[118:119], v[118:119], v[122:123]
	v_pk_add_f32 v[138:139], v[158:159], v[162:163]
	v_pk_add_f32 v[128:129], v[136:137], v[140:141]
	v_pk_add_f32 v[120:121], v[120:121], v[126:127]
	v_pk_add_f32 v[122:123], v[124:125], v[134:135]
	v_add_f32_e32 v117, v118, v119
	v_pk_add_f32 v[124:125], v[128:129], v[138:139]
	v_add_f32_e32 v118, v120, v121
	v_add_f32_e32 v119, v122, v123
	v_add_f32_dpp v117, v117, v117 quad_perm:[1,0,3,2] row_mask:0xf bank_mask:0xf bound_ctrl:1
	v_add_f32_e32 v120, v124, v125
	v_add_f32_dpp v118, v118, v118 quad_perm:[1,0,3,2] row_mask:0xf bank_mask:0xf bound_ctrl:1
	v_add_f32_dpp v119, v119, v119 quad_perm:[1,0,3,2] row_mask:0xf bank_mask:0xf bound_ctrl:1
	v_add_f32_dpp v117, v117, v117 quad_perm:[2,3,0,1] row_mask:0xf bank_mask:0xf bound_ctrl:1
	v_add_f32_dpp v120, v120, v120 quad_perm:[1,0,3,2] row_mask:0xf bank_mask:0xf bound_ctrl:1
	v_add_f32_dpp v118, v118, v118 quad_perm:[2,3,0,1] row_mask:0xf bank_mask:0xf bound_ctrl:1
	v_add_f32_dpp v119, v119, v119 quad_perm:[2,3,0,1] row_mask:0xf bank_mask:0xf bound_ctrl:1
	v_add_f32_dpp v117, v117, v117 row_half_mirror row_mask:0xf bank_mask:0xf bound_ctrl:1
	v_add_f32_dpp v120, v120, v120 quad_perm:[2,3,0,1] row_mask:0xf bank_mask:0xf bound_ctrl:1
	v_add_f32_dpp v118, v118, v118 row_half_mirror row_mask:0xf bank_mask:0xf bound_ctrl:1
	v_add_f32_dpp v119, v119, v119 row_half_mirror row_mask:0xf bank_mask:0xf bound_ctrl:1
	v_add_f32_dpp v117, v117, v117 row_mirror row_mask:0xf bank_mask:0xf bound_ctrl:1
	v_add_f32_dpp v120, v120, v120 row_half_mirror row_mask:0xf bank_mask:0xf bound_ctrl:1
	v_add_f32_dpp v118, v118, v118 row_mirror row_mask:0xf bank_mask:0xf bound_ctrl:1
	v_add_f32_dpp v119, v119, v119 row_mirror row_mask:0xf bank_mask:0xf bound_ctrl:1
	v_readlane_b32 s12, v117, 16
	v_readlane_b32 s13, v117, 48
	v_add_f32_dpp v120, v120, v120 row_mirror row_mask:0xf bank_mask:0xf bound_ctrl:1
	v_readlane_b32 s4, v117, 0
	v_readlane_b32 s5, v117, 32
	v_readlane_b32 s6, v118, 0
	v_readlane_b32 s14, v118, 16
	v_readlane_b32 s7, v118, 32
	v_readlane_b32 s15, v118, 48
	v_readlane_b32 s8, v119, 0
	v_readlane_b32 s16, v119, 16
	v_readlane_b32 s9, v119, 32
	v_readlane_b32 s17, v119, 48
	v_mov_b32_e32 v118, s12
	v_mov_b32_e32 v119, s13
	v_readlane_b32 s10, v120, 0
	v_readlane_b32 s23, v120, 16
	v_readlane_b32 s11, v120, 32
	v_readlane_b32 s25, v120, 48
	v_mov_b32_e32 v120, s14
	v_mov_b32_e32 v121, s15
	v_mov_b32_e32 v122, s16
	v_mov_b32_e32 v123, s17
	v_pk_add_f32 v[118:119], s[4:5], v[118:119]
	v_pk_add_f32 v[120:121], s[6:7], v[120:121]
	v_pk_add_f32 v[122:123], s[8:9], v[122:123]
	v_add_f32_e32 v117, v118, v119
	v_mov_b32_e32 v124, s23
	v_mov_b32_e32 v125, s25
	v_add_f32_e32 v118, v120, v121
	v_add_f32_e32 v119, v122, v123
	v_fmamk_f32 v117, v117, 0x3a800000, v115
	v_pk_add_f32 v[124:125], s[10:11], v[124:125]
	v_fmamk_f32 v118, v118, 0x3a800000, v115
	v_fmamk_f32 v119, v119, 0x3a800000, v115
	v_mul_f32_e32 v121, 0x4f800000, v117
	v_cmp_gt_f32_e64 s[8:9], s33, v117
	v_add_f32_e32 v120, v124, v125
	v_mul_f32_e32 v122, 0x4f800000, v118
	v_cmp_gt_f32_e32 vcc, s33, v118
	v_mul_f32_e32 v123, 0x4f800000, v119
	v_cmp_gt_f32_e64 s[4:5], s33, v119
	v_cndmask_b32_e64 v117, v117, v121, s[8:9]
	v_fmamk_f32 v120, v120, 0x3a800000, v115
	v_cndmask_b32_e32 v118, v118, v122, vcc
	v_cndmask_b32_e64 v119, v119, v123, s[4:5]
	v_sqrt_f32_e32 v121, v117
	v_mul_f32_e32 v124, 0x4f800000, v120
	v_cmp_gt_f32_e64 s[6:7], s33, v120
	v_sqrt_f32_e32 v122, v118
	v_sqrt_f32_e32 v123, v119
	v_cndmask_b32_e64 v120, v120, v124, s[6:7]
	v_sqrt_f32_e32 v124, v120
	v_add_u32_e32 v125, -1, v121
	v_add_u32_e32 v126, 1, v121
	v_add_u32_e32 v127, -1, v122
	v_add_u32_e32 v129, -1, v123
	v_fma_f32 v133, -v125, v121, v117
	v_add_u32_e32 v128, 1, v122
	v_add_u32_e32 v130, 1, v123
	v_fma_f32 v134, -v126, v121, v117
	v_fma_f32 v135, -v127, v122, v118
	v_fma_f32 v137, -v129, v123, v119
	v_cmp_ge_f32_e64 s[10:11], 0, v133
	v_add_u32_e32 v131, -1, v124
	v_fma_f32 v136, -v128, v122, v118
	v_fma_f32 v138, -v130, v123, v119
	v_cndmask_b32_e64 v121, v121, v125, s[10:11]
	v_cmp_ge_f32_e64 s[10:11], 0, v135
	v_cmp_ge_f32_e64 s[12:13], 0, v137
	v_cmp_lt_f32_e64 s[16:17], 0, v134
	v_add_u32_e32 v132, 1, v124
	v_fma_f32 v139, -v131, v124, v120
	v_cndmask_b32_e64 v122, v122, v127, s[10:11]
	v_cmp_lt_f32_e64 s[10:11], 0, v136
	v_cndmask_b32_e64 v123, v123, v129, s[12:13]
	v_cmp_lt_f32_e64 s[12:13], 0, v138
	v_cndmask_b32_e64 v121, v121, v126, s[16:17]
	v_fma_f32 v140, -v132, v124, v120
	v_cmp_ge_f32_e64 s[14:15], 0, v139
	v_cndmask_b32_e64 v122, v122, v128, s[10:11]
	v_cndmask_b32_e64 v123, v123, v130, s[12:13]
; __device__ __forceinline__ unsigned pk2(float lo, float hi) { f32x2 v = {lo, hi}; bf16x2_t b = __builtin_convertvector(v, bf16x2_t); return __builtin_bit_cast(unsigned, b); }
; __device__ __forceinline__ void norm_mod_phase(const Ctx& F, const float* xin, const float* gain, const float* shift, const float* scale) {
;     ...
;             for (int u = 0; u < 4; ++u) { const float rstd = 1.0f / sqrtf(s[u] * (1.0f / D) + 1e-6f);
; #pragma unroll
;                 for (int j = 0; j < 4; ++j) { const f32x4 o = v[u][j] * rstd * ga[j] + sh[j]; u32x2 w; w.x = pk2(o[0], o[1]); w.y = pk2(o[2], o[3]);
	v_mul_f32_e32 v125, 0x37800000, v121
	v_cndmask_b32_e64 v124, v124, v131, s[14:15]
	v_cmp_lt_f32_e64 s[14:15], 0, v140
	v_mul_f32_e32 v126, 0x37800000, v122
	v_mul_f32_e32 v127, 0x37800000, v123
	v_cndmask_b32_e64 v121, v121, v125, s[8:9]
	v_cmp_class_f32_e64 s[8:9], v117, v116
	v_cndmask_b32_e64 v124, v124, v132, s[14:15]
	v_cndmask_b32_e32 v122, v122, v126, vcc
	v_cmp_class_f32_e32 vcc, v118, v116
	v_cndmask_b32_e64 v123, v123, v127, s[4:5]
	v_cmp_class_f32_e64 s[4:5], v119, v116
	v_cndmask_b32_e64 v117, v121, v117, s[8:9]
	v_mul_f32_e32 v128, 0x37800000, v124
	v_cndmask_b32_e32 v121, v122, v118, vcc
	v_cndmask_b32_e64 v119, v123, v119, s[4:5]
	v_div_scale_f32 v118, s[4:5], v117, v117, 1.0
	v_cndmask_b32_e64 v124, v124, v128, s[6:7]
	v_cmp_class_f32_e64 s[6:7], v120, v116
	v_div_scale_f32 v123, s[4:5], v121, v121, 1.0
	v_rcp_f32_e32 v129, v118
	v_cndmask_b32_e64 v120, v124, v120, s[6:7]
	v_div_scale_f32 v125, s[6:7], v119, v119, 1.0
	v_rcp_f32_e32 v130, v123
	v_div_scale_f32 v127, s[8:9], v120, v120, 1.0
	v_rcp_f32_e32 v131, v125
	v_rcp_f32_e32 v132, v127
	v_fma_f32 v133, -v118, v129, 1.0
	v_div_scale_f32 v122, vcc, 1.0, v117, 1.0
	v_fma_f32 v134, -v123, v130, 1.0
	v_fmac_f32_e32 v129, v133, v129
	v_div_scale_f32 v124, s[4:5], 1.0, v121, 1.0
	v_fma_f32 v135, -v125, v131, 1.0
	v_fmac_f32_e32 v130, v134, v130
	v_mul_f32_e32 v133, v122, v129
	v_div_scale_f32 v126, s[6:7], 1.0, v119, 1.0
	v_fma_f32 v136, -v127, v132, 1.0
	v_fmac_f32_e32 v131, v135, v131
	v_mul_f32_e32 v134, v124, v130
	v_fma_f32 v137, -v118, v133, v122
	v_div_scale_f32 v128, s[8:9], 1.0, v120, 1.0
	v_fmac_f32_e32 v132, v136, v132
	v_mul_f32_e32 v135, v126, v131
	v_fma_f32 v138, -v123, v134, v124
	v_fmac_f32_e32 v133, v137, v129
	v_mul_f32_e32 v136, v128, v132
	v_fma_f32 v139, -v125, v135, v126
	v_fmac_f32_e32 v134, v138, v130
	v_fma_f32 v118, -v118, v133, v122
	v_fma_f32 v140, -v127, v136, v128
	v_fmac_f32_e32 v135, v139, v131
	v_fma_f32 v122, -v123, v134, v124
	v_div_fmas_f32 v118, v118, v129, v133
	s_mov_b64 vcc, s[4:5]
	v_fmac_f32_e32 v136, v140, v132
	v_fma_f32 v123, -v125, v135, v126
	v_div_fixup_f32 v118, v118, v117, 1.0
	v_div_fmas_f32 v117, v122, v130, v134
	s_mov_b64 vcc, s[6:7]
	v_fma_f32 v124, -v127, v136, v128
	v_pk_mul_f32 v[76:77], v[76:77], v[118:119] op_sel_hi:[1,0]
	v_pk_mul_f32 v[78:79], v[78:79], v[118:119] op_sel_hi:[1,0]
	v_pk_mul_f32 v[68:69], v[68:69], v[118:119] op_sel_hi:[1,0]
	v_pk_mul_f32 v[70:71], v[70:71], v[118:119] op_sel_hi:[1,0]
	v_pk_mul_f32 v[72:73], v[72:73], v[118:119] op_sel_hi:[1,0]
	v_pk_mul_f32 v[74:75], v[74:75], v[118:119] op_sel_hi:[1,0]
	v_pk_mul_f32 v[64:65], v[64:65], v[118:119] op_sel_hi:[1,0]
	v_pk_mul_f32 v[66:67], v[66:67], v[118:119] op_sel_hi:[1,0]
	v_div_fixup_f32 v118, v117, v121, 1.0
	v_div_fmas_f32 v117, v123, v131, v135
	s_mov_b64 vcc, s[8:9]
	v_pk_mul_f32 v[60:61], v[60:61], v[118:119] op_sel_hi:[1,0]
	v_pk_mul_f32 v[62:63], v[62:63], v[118:119] op_sel_hi:[1,0]
	v_pk_mul_f32 v[56:57], v[56:57], v[118:119] op_sel_hi:[1,0]
	v_pk_mul_f32 v[58:59], v[58:59], v[118:119] op_sel_hi:[1,0]
	v_pk_mul_f32 v[52:53], v[52:53], v[118:119] op_sel_hi:[1,0]
	v_pk_mul_f32 v[54:55], v[54:55], v[118:119] op_sel_hi:[1,0]
	v_pk_mul_f32 v[48:49], v[48:49], v[118:119] op_sel_hi:[1,0]
	v_pk_mul_f32 v[50:51], v[50:51], v[118:119] op_sel_hi:[1,0]
	v_div_fixup_f32 v118, v117, v119, 1.0
	v_pk_fma_f32 v[66:67], v[102:103], v[66:67], v[14:15]
	v_pk_fma_f32 v[64:65], v[104:105], v[64:65], v[12:13]
	v_div_fmas_f32 v117, v124, v132, v136
	v_cvt_pk_bf16_f32 v64, v64, v65
	v_cvt_pk_bf16_f32 v65, v66, v67
	v_div_fixup_f32 v66, v117, v120, 1.0
	v_pk_mul_f32 v[44:45], v[44:45], v[118:119] op_sel_hi:[1,0]
	v_pk_mul_f32 v[46:47], v[46:47], v[118:119] op_sel_hi:[1,0]
	v_pk_mul_f32 v[24:25], v[24:25], v[66:67] op_sel_hi:[1,0]
	v_pk_mul_f32 v[26:27], v[26:27], v[66:67] op_sel_hi:[1,0]
	v_pk_fma_f32 v[78:79], v[90:91], v[78:79], v[2:3]
	v_pk_fma_f32 v[76:77], v[92:93], v[76:77], v[0:1]
	v_pk_mul_f32 v[40:41], v[40:41], v[118:119] op_sel_hi:[1,0]
	v_pk_mul_f32 v[42:43], v[42:43], v[118:119] op_sel_hi:[1,0]
	v_pk_mul_f32 v[36:37], v[36:37], v[118:119] op_sel_hi:[1,0]
; __device__ __forceinline__ unsigned pk2(float lo, float hi) { f32x2 v = {lo, hi}; bf16x2_t b = __builtin_convertvector(v, bf16x2_t); return __builtin_bit_cast(unsigned, b); }
; __device__ __forceinline__ void norm_mod_phase(const Ctx& F, const float* xin, const float* gain, const float* shift, const float* scale) {
;     ...
;     for (int ch = gw; ch < T / 32; ch += NGW) {
;     ...
;                 for (int j = 0; j < 4; ++j) { const f32x4 o = v[u][j] * rstd * ga[j] + sh[j]; u32x2 w; w.x = pk2(o[0], o[1]); w.y = pk2(o[2], o[3]);
;                     *(u32x2*)(hb + (size_t)(row0 + r + u) * D + 4 * ln + 256 * j) = w; } }
;         }
	v_pk_mul_f32 v[38:39], v[38:39], v[118:119] op_sel_hi:[1,0]
	v_pk_mul_f32 v[32:33], v[32:33], v[118:119] op_sel_hi:[1,0]
	v_pk_mul_f32 v[34:35], v[34:35], v[118:119] op_sel_hi:[1,0]
	v_pk_fma_f32 v[62:63], v[90:91], v[62:63], v[2:3]
	v_pk_fma_f32 v[60:61], v[92:93], v[60:61], v[0:1]
	v_pk_mul_f32 v[20:21], v[20:21], v[66:67] op_sel_hi:[1,0]
	v_pk_mul_f32 v[22:23], v[22:23], v[66:67] op_sel_hi:[1,0]
	v_pk_mul_f32 v[16:17], v[16:17], v[66:67] op_sel_hi:[1,0]
	v_pk_mul_f32 v[18:19], v[18:19], v[66:67] op_sel_hi:[1,0]
	v_pk_mul_f32 v[28:29], v[28:29], v[66:67] op_sel_hi:[1,0]
	v_pk_mul_f32 v[30:31], v[30:31], v[66:67] op_sel_hi:[1,0]
	v_pk_fma_f32 v[46:47], v[90:91], v[46:47], v[2:3]
	v_pk_fma_f32 v[44:45], v[92:93], v[44:45], v[0:1]
	v_pk_fma_f32 v[26:27], v[90:91], v[26:27], v[2:3]
	v_pk_fma_f32 v[24:25], v[92:93], v[24:25], v[0:1]
	v_pk_fma_f32 v[70:71], v[94:95], v[70:71], v[6:7]
	v_pk_fma_f32 v[68:69], v[96:97], v[68:69], v[4:5]
	v_pk_fma_f32 v[74:75], v[98:99], v[74:75], v[10:11]
	v_pk_fma_f32 v[72:73], v[100:101], v[72:73], v[8:9]
	v_cvt_pk_bf16_f32 v76, v76, v77
	v_cvt_pk_bf16_f32 v77, v78, v79
	v_pk_fma_f32 v[58:59], v[94:95], v[58:59], v[6:7]
	v_pk_fma_f32 v[56:57], v[96:97], v[56:57], v[4:5]
	v_pk_fma_f32 v[54:55], v[98:99], v[54:55], v[10:11]
	v_pk_fma_f32 v[52:53], v[100:101], v[52:53], v[8:9]
	v_pk_fma_f32 v[50:51], v[102:103], v[50:51], v[14:15]
	v_pk_fma_f32 v[48:49], v[104:105], v[48:49], v[12:13]
	v_cvt_pk_bf16_f32 v60, v60, v61
	v_cvt_pk_bf16_f32 v61, v62, v63
	v_pk_fma_f32 v[42:43], v[94:95], v[42:43], v[6:7]
	v_pk_fma_f32 v[40:41], v[96:97], v[40:41], v[4:5]
	v_pk_fma_f32 v[38:39], v[98:99], v[38:39], v[10:11]
	v_pk_fma_f32 v[36:37], v[100:101], v[36:37], v[8:9]
	v_pk_fma_f32 v[34:35], v[102:103], v[34:35], v[14:15]
	v_pk_fma_f32 v[32:33], v[104:105], v[32:33], v[12:13]
	v_cvt_pk_bf16_f32 v44, v44, v45
	v_cvt_pk_bf16_f32 v45, v46, v47
	v_pk_fma_f32 v[22:23], v[94:95], v[22:23], v[6:7]
	v_pk_fma_f32 v[20:21], v[96:97], v[20:21], v[4:5]
	v_pk_fma_f32 v[18:19], v[98:99], v[18:19], v[10:11]
	v_pk_fma_f32 v[16:17], v[100:101], v[16:17], v[8:9]
	v_pk_fma_f32 v[30:31], v[102:103], v[30:31], v[14:15]
	v_pk_fma_f32 v[28:29], v[104:105], v[28:29], v[12:13]
	v_cvt_pk_bf16_f32 v24, v24, v25
	v_cvt_pk_bf16_f32 v25, v26, v27
	v_cvt_pk_bf16_f32 v68, v68, v69
	v_cvt_pk_bf16_f32 v69, v70, v71
	v_cvt_pk_bf16_f32 v70, v72, v73
	v_cvt_pk_bf16_f32 v71, v74, v75
	global_store_dwordx2 v[112:113], v[76:77], off
	global_store_dwordx2 v[112:113], v[68:69], off offset:512
	global_store_dwordx2 v[112:113], v[70:71], off offset:1024
	global_store_dwordx2 v[112:113], v[64:65], off offset:1536
	v_cvt_pk_bf16_f32 v56, v56, v57
	v_cvt_pk_bf16_f32 v57, v58, v59
	v_cvt_pk_bf16_f32 v52, v52, v53
	v_cvt_pk_bf16_f32 v53, v54, v55
	v_cvt_pk_bf16_f32 v48, v48, v49
	v_cvt_pk_bf16_f32 v49, v50, v51
	global_store_dwordx2 v[110:111], v[60:61], off
	global_store_dwordx2 v[110:111], v[56:57], off offset:512
	global_store_dwordx2 v[110:111], v[52:53], off offset:1024
	global_store_dwordx2 v[110:111], v[48:49], off offset:1536
	v_cvt_pk_bf16_f32 v40, v40, v41
	v_cvt_pk_bf16_f32 v41, v42, v43
	v_cvt_pk_bf16_f32 v36, v36, v37
	v_cvt_pk_bf16_f32 v37, v38, v39
	v_cvt_pk_bf16_f32 v32, v32, v33
	v_cvt_pk_bf16_f32 v33, v34, v35
	global_store_dwordx2 v[108:109], v[44:45], off
	global_store_dwordx2 v[108:109], v[40:41], off offset:512
	global_store_dwordx2 v[108:109], v[36:37], off offset:1024
	global_store_dwordx2 v[108:109], v[32:33], off offset:1536
	v_cvt_pk_bf16_f32 v20, v20, v21
	v_cvt_pk_bf16_f32 v21, v22, v23
	v_cvt_pk_bf16_f32 v16, v16, v17
	v_cvt_pk_bf16_f32 v17, v18, v19
	v_cvt_pk_bf16_f32 v18, v28, v29
	v_cvt_pk_bf16_f32 v19, v30, v31
	global_store_dwordx2 v[106:107], v[24:25], off
	global_store_dwordx2 v[106:107], v[20:21], off offset:512
	global_store_dwordx2 v[106:107], v[16:17], off offset:1024
	global_store_dwordx2 v[106:107], v[18:19], off offset:1536
	s_cbranch_scc0 .LBB0_164
	s_add_i32 s0, s0, s1
	s_add_i32 s20, s20, s3
	s_add_i32 s22, s22, s3
	s_add_i32 s24, s24, s3
	s_add_i32 s26, s26, s3
	s_cmpk_gt_i32 s0, 0x7ff
	s_cbranch_scc0 .LBB0_163
